# attention main line: QK^T chains reordered (keys 0-31 first), the exp2 and row-sum work on that chain's scores issued between the second chain's MFMAs (MFMA shadow); same scores, same P
# speedup vs baseline: 1.0049x; 1.0025x over previous
; DI float fexp2(float x) { return __builtin_amdgcn_exp2f(x); }
; DI void phase_attn(const Params& p, int hf, bool skipctx, char* smem, int& rot) {
;     ...
;     auto compute = [&](int buf, int half) {
;       const char* sk = smem + buf * STG + half * 64 * KROW; const char* sv = smem + buf * STG + KB_ + half * 128;
;       f32x16 st[2]; st[0] = zero16(); st[1] = zero16();
;       {
;         bf16x8 kf[2][6];
; #pragma unroll
;         for (int kb = 0; kb < 2; ++kb)
; #pragma unroll
;           for (int ks = 0; ks < 6; ++ks) kf[kb][ks] = *(const bf16x8*)(sk + (kb * 32 + r) * KROW + (ks * 16 + h * 8) * 2);
;         __builtin_amdgcn_sched_barrier(0);
; #pragma unroll
;         for (int ks = 0; ks < 6; ++ks)
; #pragma unroll
;           for (int kb = 0; kb < 2; ++kb) st[kb] = MFMA(kf[kb][ks], qf[ks], st[kb]);
;         __builtin_amdgcn_sched_barrier(0);
;       }
;       bf16x8 vf[2][2][2];
; #pragma unroll
;       for (int kb = 0; kb < 2; ++kb)
; #pragma unroll
;         for (int s2 = 0; s2 < 2; ++s2)
; #pragma unroll
;           for (int dvb = 0; dvb < 2; ++dvb) {
;             const char* vp = sv + (dvb * 32 + r) * VROW + (kb * 32 + 16 * s2 + 4 * h) * 2;
;             const s16x4 lo = *(const s16x4*)vp, hi = *(const s16x4*)(vp + 16);
;             vf[kb][s2][dvb] = __builtin_shufflevector(lo, hi, 0, 1, 2, 3, 4, 5, 6, 7);
;           }
;       float mx = st[0][0];
; #pragma unroll
;       for (int i = 0; i < 16; ++i) { mx = fmaxf(mx, st[0][i]); mx = fmaxf(mx, st[1][i]); }
;       if (__any(mx > m_run + 8.f)) {
;         mx = fmaxf(mx, __shfl_xor(mx, 32));
;         const float m_new = fmaxf(m_run, mx);
;         const float alpha = fexp2(m_run - m_new);
;         m_run = m_new;
;         l_run *= alpha;
; #pragma unroll
;         for (int i = 0; i < 16; ++i) { o[0][i] *= alpha; o[1][i] *= alpha; }
;       }
;       float ps = 0.f;
; #pragma unroll
;       for (int kb = 0; kb < 2; ++kb)
; #pragma unroll
;         for (int i = 0; i < 16; ++i) { const float e = fexp2(st[kb][i] - m_run); st[kb][i] = e; ps += e; }
;       l_run += ps;
; #pragma unroll
;       for (int kb = 0; kb < 2; ++kb)
; #pragma unroll
;         for (int s2 = 0; s2 < 2; ++s2) {
;           const bf16x8 pb = pack8(st[kb][8 * s2 + 0], st[kb][8 * s2 + 1], st[kb][8 * s2 + 2], st[kb][8 * s2 + 3], st[kb][8 * s2 + 4], st[kb][8 * s2 + 5], st[kb][8 * s2 + 6], st[kb][8 * s2 + 7]);
; #pragma unroll
.LBB0_797:
	s_cmp_eq_u32 s101, 0
	s_cbranch_scc1 .Lsc0_fb0e
	s_waitcnt lgkmcnt(11)
	v_mfma_f32_32x32x16_bf16 v[48:63], v[32:35], v[64:67], v[176:191]
	s_waitcnt lgkmcnt(10)
	v_mfma_f32_32x32x16_bf16 v[48:63], v[128:131], v[68:71], v[48:63]
	s_waitcnt lgkmcnt(9)
	v_mfma_f32_32x32x16_bf16 v[48:63], v[132:135], v[72:75], v[48:63]
	s_waitcnt lgkmcnt(8)
	v_mfma_f32_32x32x16_bf16 v[48:63], v[136:139], v[88:91], v[48:63]
	s_waitcnt lgkmcnt(7)
	v_mfma_f32_32x32x16_bf16 v[48:63], v[140:143], v[96:99], v[48:63]
	s_waitcnt lgkmcnt(6)
	v_mfma_f32_32x32x16_bf16 v[48:63], v[144:147], v[100:103], v[48:63]
	s_waitcnt lgkmcnt(5)
	v_mfma_f32_32x32x16_bf16 v[32:47], v[36:39], v[64:67], v[176:191]
	s_waitcnt lgkmcnt(4)
	v_mfma_f32_32x32x16_bf16 v[32:47], v[148:151], v[68:71], v[32:47]
	s_nop 11
	v_exp_f32_e32 v48, v48
	v_exp_f32_e32 v49, v49
	v_exp_f32_e32 v50, v50
	v_exp_f32_e32 v51, v51
	v_exp_f32_e32 v52, v52
	v_exp_f32_e32 v53, v53
	v_exp_f32_e32 v54, v54
	v_exp_f32_e32 v55, v55
	s_waitcnt lgkmcnt(3)
	v_mfma_f32_32x32x16_bf16 v[32:47], v[152:155], v[72:75], v[32:47]
	v_exp_f32_e32 v56, v56
	v_exp_f32_e32 v57, v57
	v_exp_f32_e32 v58, v58
	v_exp_f32_e32 v59, v59
	v_exp_f32_e32 v60, v60
	v_exp_f32_e32 v61, v61
	v_exp_f32_e32 v62, v62
	v_exp_f32_e32 v63, v63
	s_waitcnt lgkmcnt(2)
	v_mfma_f32_32x32x16_bf16 v[32:47], v[156:159], v[88:91], v[32:47]
	v_add_f32_e32 v195, v48, v49
	v_add_f32_e32 v195, v195, v50
	v_add_f32_e32 v195, v195, v51
	v_add_f32_e32 v195, v195, v52
	v_add_f32_e32 v195, v195, v53
	v_add_f32_e32 v195, v195, v54
	v_add_f32_e32 v195, v195, v55
	v_add_f32_e32 v195, v195, v56
	s_waitcnt lgkmcnt(1)
	v_mfma_f32_32x32x16_bf16 v[32:47], v[214:217], v[96:99], v[32:47]
	v_add_f32_e32 v195, v195, v57
	v_add_f32_e32 v195, v195, v58
	v_add_f32_e32 v195, v195, v59
	v_add_f32_e32 v195, v195, v60
	v_add_f32_e32 v195, v195, v61
	v_add_f32_e32 v195, v195, v62
	v_add_f32_e32 v195, v195, v63
	s_waitcnt lgkmcnt(0)
	v_mfma_f32_32x32x16_bf16 v[32:47], v[234:237], v[100:103], v[32:47]
	s_nop 3
	ds_read_b128 v[156:159], v211 offset:0
	ds_read_b128 v[148:151], v211 offset:32
	ds_read_b128 v[152:155], v211 offset:8704
	ds_read_b128 v[144:147], v211 offset:8736
	ds_read_b128 v[140:143], v211 offset:64
	ds_read_b128 v[136:139], v211 offset:8768
	ds_read_b128 v[132:135], v211 offset:96
	ds_read_b128 v[128:131], v211 offset:8800
	v_exp_f32_e32 v32, v32
	v_exp_f32_e32 v33, v33
	v_exp_f32_e32 v34, v34
	v_exp_f32_e32 v35, v35
	v_exp_f32_e32 v36, v36
	v_exp_f32_e32 v37, v37
	v_exp_f32_e32 v38, v38
	v_exp_f32_e32 v39, v39
	v_exp_f32_e32 v40, v40
	v_exp_f32_e32 v41, v41
	v_exp_f32_e32 v42, v42
	v_exp_f32_e32 v43, v43
	v_exp_f32_e32 v44, v44
	v_exp_f32_e32 v45, v45
	v_exp_f32_e32 v46, v46
	v_exp_f32_e32 v47, v47
	v_add_f32_e32 v195, v195, v32
	v_add_f32_e32 v195, v195, v33
	v_add_f32_e32 v195, v195, v34
	v_add_f32_e32 v195, v195, v35
	v_add_f32_e32 v195, v195, v36
	v_add_f32_e32 v195, v195, v37
	v_add_f32_e32 v195, v195, v38
	v_add_f32_e32 v195, v195, v39
	v_add_f32_e32 v195, v195, v40
	v_add_f32_e32 v195, v195, v41
	v_add_f32_e32 v195, v195, v42
	v_add_f32_e32 v195, v195, v43
	v_add_f32_e32 v195, v195, v44
	v_add_f32_e32 v195, v195, v45
	v_add_f32_e32 v195, v195, v46
	v_add_f32_e32 v195, v195, v47
	v_cmp_nle_f32_e32 vcc, v195, v167
	s_cbranch_vccnz .Lsc0_fb0
	v_add_f32_e32 v213, v213, v195
	v_cvt_pk_bf16_f32 v48, v48, v49
	v_cvt_pk_bf16_f32 v49, v50, v51
	v_cvt_pk_bf16_f32 v50, v52, v53
	v_cvt_pk_bf16_f32 v51, v54, v55
	v_cvt_pk_bf16_f32 v52, v56, v57
	v_cvt_pk_bf16_f32 v53, v58, v59
	v_cvt_pk_bf16_f32 v54, v60, v61
	v_cvt_pk_bf16_f32 v55, v62, v63
	v_cvt_pk_bf16_f32 v56, v32, v33
	v_cvt_pk_bf16_f32 v57, v34, v35
	v_cvt_pk_bf16_f32 v58, v36, v37
	v_cvt_pk_bf16_f32 v59, v38, v39
	v_cvt_pk_bf16_f32 v60, v40, v41
	v_cvt_pk_bf16_f32 v61, v42, v43
	v_cvt_pk_bf16_f32 v62, v44, v45
	v_cvt_pk_bf16_f32 v63, v46, v47
	s_waitcnt lgkmcnt(7)
	v_mfma_f32_32x32x16_bf16 v[16:31], v[156:159], v[48:51], v[16:31]
	s_waitcnt lgkmcnt(5)
	v_mfma_f32_32x32x16_bf16 v[0:15], v[152:155], v[48:51], v[0:15]
	s_nop 0
	v_mfma_f32_32x32x16_bf16 v[16:31], v[148:151], v[52:55], v[16:31]
	s_waitcnt lgkmcnt(4)
	v_mfma_f32_32x32x16_bf16 v[0:15], v[144:147], v[52:55], v[0:15]
	s_waitcnt lgkmcnt(3)
	v_mfma_f32_32x32x16_bf16 v[16:31], v[140:143], v[56:59], v[16:31]
	s_waitcnt lgkmcnt(2)
	v_mfma_f32_32x32x16_bf16 v[0:15], v[136:139], v[56:59], v[0:15]
	s_waitcnt lgkmcnt(1)
	s_nop 0
	v_mfma_f32_32x32x16_bf16 v[16:31], v[132:135], v[60:63], v[16:31]
	ds_read_b128 v[36:39], v210 offset:13312
	ds_read_b128 v[132:135], v210 offset:13344
	ds_read_b128 v[136:139], v210 offset:13376
	ds_read_b128 v[140:143], v210 offset:13408
	ds_read_b128 v[144:147], v210 offset:13440
	ds_read_b128 v[148:151], v210 offset:13472
	ds_read_b128 v[40:43], v210 offset:19968
	ds_read_b128 v[152:155], v210 offset:20000
	ds_read_b128 v[156:159], v210 offset:20032
	ds_read_b128 v[234:237], v210 offset:20064
	ds_read_b128 v[238:241], v210 offset:20096
	ds_read_b128 v[242:245], v210 offset:20128
	s_waitcnt lgkmcnt(12)
	v_mfma_f32_32x32x16_bf16 v[0:15], v[128:131], v[60:63], v[0:15]
; DI float fexp2(float x) { return __builtin_amdgcn_exp2f(x); }
; DI void phase_attn(const Params& p, int hf, bool skipctx, char* smem, int& rot) {
;     ...
;           for (int kb = 0; kb < 2; ++kb) st[kb] = MFMA(kf[kb][ks], qf[ks], st[kb]);
;         __builtin_amdgcn_sched_barrier(0);
;       }
;       bf16x8 vf[2][2][2];
; #pragma unroll
;       for (int kb = 0; kb < 2; ++kb)
; #pragma unroll
;         for (int s2 = 0; s2 < 2; ++s2)
; #pragma unroll
;           for (int dvb = 0; dvb < 2; ++dvb) {
;             const char* vp = sv + (dvb * 32 + r) * VROW + (kb * 32 + 16 * s2 + 4 * h) * 2;
;             const s16x4 lo = *(const s16x4*)vp, hi = *(const s16x4*)(vp + 16);
;             vf[kb][s2][dvb] = __builtin_shufflevector(lo, hi, 0, 1, 2, 3, 4, 5, 6, 7);
;           }
;       float mx = st[0][0];
; #pragma unroll
;       for (int i = 0; i < 16; ++i) { mx = fmaxf(mx, st[0][i]); mx = fmaxf(mx, st[1][i]); }
;       if (__any(mx > m_run + 8.f)) {
;         mx = fmaxf(mx, __shfl_xor(mx, 32));
;         const float m_new = fmaxf(m_run, mx);
;         const float alpha = fexp2(m_run - m_new);
;         m_run = m_new;
;         l_run *= alpha;
; #pragma unroll
;         for (int i = 0; i < 16; ++i) { o[0][i] *= alpha; o[1][i] *= alpha; }
;       }
;       float ps = 0.f;
; #pragma unroll
;       for (int kb = 0; kb < 2; ++kb)
; #pragma unroll
;         for (int i = 0; i < 16; ++i) { const float e = fexp2(st[kb][i] - m_run); st[kb][i] = e; ps += e; }
;       l_run += ps;
; #pragma unroll
;       for (int kb = 0; kb < 2; ++kb)
; #pragma unroll
;         for (int s2 = 0; s2 < 2; ++s2) {
;           const bf16x8 pb = pack8(st[kb][8 * s2 + 0], st[kb][8 * s2 + 1], st[kb][8 * s2 + 2], st[kb][8 * s2 + 3], st[kb][8 * s2 + 4], st[kb][8 * s2 + 5], st[kb][8 * s2 + 6], st[kb][8 * s2 + 7]);
; #pragma unroll
;           for (int dvb = 0; dvb < 2; ++dvb) o[dvb] = MFMA(vf[kb][s2][dvb], pb, o[dvb]);
;         }
;     };
;     __syncthreads();
;     ATT_LOAD(ak0, ak1, ak2, av0, av1, 0);
;     ATT_LOAD(bk0, bk1, bk2, bv0, bv1, 1);
;     ATT_WRITE(ak0, ak1, ak2, av0, av1, 0);
;     __syncthreads();
;     for (int kt = 0; kt < nkt; kt += 2) {
;       if (kt + 2 < nkt) ATT_LOAD(ak0, ak1, ak2, av0, av1, kt + 2);
;       compute(0, 0); compute(0, 1);
;       ATT_WRITE(bk0, bk1, bk2, bv0, bv1, 1);
;       __syncthreads();
;       if (kt + 3 < nkt) ATT_LOAD(bk0, bk1, bk2, bv0, bv1, kt + 3);
.Lsc0_mj0:
	s_waitcnt lgkmcnt(11)
	v_mfma_f32_32x32x16_bf16 v[48:63], v[36:39], v[64:67], v[176:191]
	s_waitcnt lgkmcnt(10)
	v_mfma_f32_32x32x16_bf16 v[48:63], v[132:135], v[68:71], v[48:63]
	s_waitcnt lgkmcnt(9)
	v_mfma_f32_32x32x16_bf16 v[48:63], v[136:139], v[72:75], v[48:63]
	s_waitcnt lgkmcnt(8)
	v_mfma_f32_32x32x16_bf16 v[48:63], v[140:143], v[88:91], v[48:63]
	s_waitcnt lgkmcnt(7)
	v_mfma_f32_32x32x16_bf16 v[48:63], v[144:147], v[96:99], v[48:63]
	s_waitcnt lgkmcnt(6)
	v_mfma_f32_32x32x16_bf16 v[48:63], v[148:151], v[100:103], v[48:63]
	s_waitcnt lgkmcnt(5)
	v_mfma_f32_32x32x16_bf16 v[32:47], v[40:43], v[64:67], v[176:191]
	s_waitcnt lgkmcnt(4)
	v_mfma_f32_32x32x16_bf16 v[32:47], v[152:155], v[68:71], v[32:47]
	s_nop 11
	v_exp_f32_e32 v48, v48
	v_exp_f32_e32 v49, v49
	v_exp_f32_e32 v50, v50
	v_exp_f32_e32 v51, v51
	v_exp_f32_e32 v52, v52
	v_exp_f32_e32 v53, v53
	v_exp_f32_e32 v54, v54
	v_exp_f32_e32 v55, v55
	s_waitcnt lgkmcnt(3)
	v_mfma_f32_32x32x16_bf16 v[32:47], v[156:159], v[72:75], v[32:47]
	v_exp_f32_e32 v56, v56
	v_exp_f32_e32 v57, v57
	v_exp_f32_e32 v58, v58
	v_exp_f32_e32 v59, v59
	v_exp_f32_e32 v60, v60
	v_exp_f32_e32 v61, v61
	v_exp_f32_e32 v62, v62
	v_exp_f32_e32 v63, v63
	s_waitcnt lgkmcnt(2)
	v_mfma_f32_32x32x16_bf16 v[32:47], v[234:237], v[88:91], v[32:47]
	v_add_f32_e32 v195, v48, v49
	v_add_f32_e32 v195, v195, v50
	v_add_f32_e32 v195, v195, v51
	v_add_f32_e32 v195, v195, v52
	v_add_f32_e32 v195, v195, v53
	v_add_f32_e32 v195, v195, v54
	v_add_f32_e32 v195, v195, v55
	v_add_f32_e32 v195, v195, v56
	s_waitcnt lgkmcnt(1)
	v_mfma_f32_32x32x16_bf16 v[32:47], v[238:241], v[96:99], v[32:47]
	v_add_f32_e32 v195, v195, v57
	v_add_f32_e32 v195, v195, v58
	v_add_f32_e32 v195, v195, v59
	v_add_f32_e32 v195, v195, v60
	v_add_f32_e32 v195, v195, v61
	v_add_f32_e32 v195, v195, v62
	v_add_f32_e32 v195, v195, v63
	s_waitcnt lgkmcnt(0)
	v_mfma_f32_32x32x16_bf16 v[32:47], v[242:245], v[100:103], v[32:47]
	s_nop 3
	ds_read_b128 v[156:159], v211 offset:128
	ds_read_b128 v[148:151], v211 offset:160
	ds_read_b128 v[152:155], v211 offset:8832
	ds_read_b128 v[144:147], v211 offset:8864
	ds_read_b128 v[140:143], v211 offset:192
	ds_read_b128 v[136:139], v211 offset:8896
	ds_read_b128 v[128:131], v211 offset:224
	ds_read_b128 v[132:135], v211 offset:8928
	v_exp_f32_e32 v32, v32
	v_exp_f32_e32 v33, v33
	v_exp_f32_e32 v34, v34
	v_exp_f32_e32 v35, v35
	v_exp_f32_e32 v36, v36
	v_exp_f32_e32 v37, v37
	v_exp_f32_e32 v38, v38
	v_exp_f32_e32 v39, v39
	v_exp_f32_e32 v40, v40
	v_exp_f32_e32 v41, v41
	v_exp_f32_e32 v42, v42
	v_exp_f32_e32 v43, v43
	v_exp_f32_e32 v44, v44
	v_exp_f32_e32 v45, v45
	v_exp_f32_e32 v46, v46
	v_exp_f32_e32 v47, v47
	v_add_f32_e32 v195, v195, v32
	v_add_f32_e32 v195, v195, v33
	v_add_f32_e32 v195, v195, v34
	v_add_f32_e32 v195, v195, v35
	v_add_f32_e32 v195, v195, v36
	v_add_f32_e32 v195, v195, v37
	v_add_f32_e32 v195, v195, v38
	v_add_f32_e32 v195, v195, v39
	v_add_f32_e32 v195, v195, v40
	v_add_f32_e32 v195, v195, v41
	v_add_f32_e32 v195, v195, v42
	v_add_f32_e32 v195, v195, v43
	v_add_f32_e32 v195, v195, v44
	v_add_f32_e32 v195, v195, v45
	v_add_f32_e32 v195, v195, v46
	v_add_f32_e32 v195, v195, v47
	v_cmp_nle_f32_e32 vcc, v195, v167
	s_cbranch_vccnz .Lsc0_fb1
	v_add_f32_e32 v213, v213, v195
	v_cvt_pk_bf16_f32 v48, v48, v49
	v_cvt_pk_bf16_f32 v49, v50, v51
	v_cvt_pk_bf16_f32 v50, v52, v53
	v_cvt_pk_bf16_f32 v51, v54, v55
	v_cvt_pk_bf16_f32 v52, v56, v57
	v_cvt_pk_bf16_f32 v53, v58, v59
	v_cvt_pk_bf16_f32 v54, v60, v61
	v_cvt_pk_bf16_f32 v55, v62, v63
	v_cvt_pk_bf16_f32 v56, v32, v33
	v_cvt_pk_bf16_f32 v57, v34, v35
	v_cvt_pk_bf16_f32 v58, v36, v37
	v_cvt_pk_bf16_f32 v59, v38, v39
	v_cvt_pk_bf16_f32 v60, v40, v41
	v_cvt_pk_bf16_f32 v61, v42, v43
	v_cvt_pk_bf16_f32 v62, v44, v45
	v_cvt_pk_bf16_f32 v63, v46, v47
	s_waitcnt lgkmcnt(7)
	s_nop 0
	v_mfma_f32_32x32x16_bf16 v[16:31], v[156:159], v[48:51], v[16:31]
	s_waitcnt lgkmcnt(5)
	v_mfma_f32_32x32x16_bf16 v[0:15], v[152:155], v[48:51], v[0:15]
	s_nop 1
	v_mfma_f32_32x32x16_bf16 v[16:31], v[148:151], v[52:55], v[16:31]
	s_waitcnt lgkmcnt(4)
	v_mfma_f32_32x32x16_bf16 v[0:15], v[144:147], v[52:55], v[0:15]
	s_waitcnt lgkmcnt(3)
	s_nop 0
	v_mfma_f32_32x32x16_bf16 v[16:31], v[140:143], v[56:59], v[16:31]
	s_waitcnt lgkmcnt(2)
	v_mfma_f32_32x32x16_bf16 v[0:15], v[136:139], v[56:59], v[0:15]
	s_add_i32 s4, s4, 3
	s_cmp_ge_u32 s4, s13
	s_waitcnt lgkmcnt(1)
	v_mfma_f32_32x32x16_bf16 v[16:31], v[128:131], v[60:63], v[16:31]
	s_waitcnt vmcnt(1)
	ds_write_b128 v194, v[112:115] offset:44032
	ds_write_b128 v204, v[108:111] offset:44032
	ds_write_b128 v206, v[116:119] offset:44032
	ds_write_b64 v208, v[120:121] offset:44032
	ds_write_b64 v208, v[122:123] offset:44048
	s_waitcnt vmcnt(0)
	ds_write_b64 v208, v[124:125] offset:52736
	ds_write_b64 v208, v[126:127] offset:52752
	s_waitcnt lgkmcnt(0)
	s_barrier
	v_mfma_f32_32x32x16_bf16 v[0:15], v[132:135], v[60:63], v[0:15]
	s_cbranch_scc1 .LBB0_803
	v_add_u32_e32 v200, 0x6000, v174
	v_add_u32_e32 v201, 0x6000, v172
	v_add_u32_e32 v202, 0x6000, v170
	global_load_dwordx4 v[112:115], v200, s[94:95]
	global_load_dwordx4 v[108:111], v201, s[94:95]
	global_load_dwordx4 v[116:119], v202, s[94:95]
	global_load_dwordx4 v[120:123], v166, s[94:95]
	global_load_dwordx4 v[124:127], v168, s[94:95]

; DI float fexp2(float x) { return __builtin_amdgcn_exp2f(x); }
; DI void phase_attn(const Params& p, int hf, bool skipctx, char* smem, int& rot) {
;     ...
;     auto compute = [&](int buf, int half) {
;       const char* sk = smem + buf * STG + half * 64 * KROW; const char* sv = smem + buf * STG + KB_ + half * 128;
;       f32x16 st[2]; st[0] = zero16(); st[1] = zero16();
;       {
;         bf16x8 kf[2][6];
; #pragma unroll
;         for (int kb = 0; kb < 2; ++kb)
; #pragma unroll
;           for (int ks = 0; ks < 6; ++ks) kf[kb][ks] = *(const bf16x8*)(sk + (kb * 32 + r) * KROW + (ks * 16 + h * 8) * 2);
;         __builtin_amdgcn_sched_barrier(0);
; #pragma unroll
;         for (int ks = 0; ks < 6; ++ks)
; #pragma unroll
;           for (int kb = 0; kb < 2; ++kb) st[kb] = MFMA(kf[kb][ks], qf[ks], st[kb]);
;         __builtin_amdgcn_sched_barrier(0);
;       }
;       bf16x8 vf[2][2][2];
; #pragma unroll
;       for (int kb = 0; kb < 2; ++kb)
; #pragma unroll
;         for (int s2 = 0; s2 < 2; ++s2)
; #pragma unroll
;           for (int dvb = 0; dvb < 2; ++dvb) {
;             const char* vp = sv + (dvb * 32 + r) * VROW + (kb * 32 + 16 * s2 + 4 * h) * 2;
;             const s16x4 lo = *(const s16x4*)vp, hi = *(const s16x4*)(vp + 16);
;             vf[kb][s2][dvb] = __builtin_shufflevector(lo, hi, 0, 1, 2, 3, 4, 5, 6, 7);
;           }
;       float mx = st[0][0];
; #pragma unroll
;       for (int i = 0; i < 16; ++i) { mx = fmaxf(mx, st[0][i]); mx = fmaxf(mx, st[1][i]); }
;       if (__any(mx > m_run + 8.f)) {
;         mx = fmaxf(mx, __shfl_xor(mx, 32));
;         const float m_new = fmaxf(m_run, mx);
;         const float alpha = fexp2(m_run - m_new);
;         m_run = m_new;
;         l_run *= alpha;
; #pragma unroll
;         for (int i = 0; i < 16; ++i) { o[0][i] *= alpha; o[1][i] *= alpha; }
;       }
;       float ps = 0.f;
; #pragma unroll
;       for (int kb = 0; kb < 2; ++kb)
; #pragma unroll
;         for (int i = 0; i < 16; ++i) { const float e = fexp2(st[kb][i] - m_run); st[kb][i] = e; ps += e; }
;       l_run += ps;
; #pragma unroll
;       for (int kb = 0; kb < 2; ++kb)
; #pragma unroll
;         for (int s2 = 0; s2 < 2; ++s2) {
;           const bf16x8 pb = pack8(st[kb][8 * s2 + 0], st[kb][8 * s2 + 1], st[kb][8 * s2 + 2], st[kb][8 * s2 + 3], st[kb][8 * s2 + 4], st[kb][8 * s2 + 5], st[kb][8 * s2 + 6], st[kb][8 * s2 + 7]);
; #pragma unroll
.Lsc0_mj1:
	s_waitcnt lgkmcnt(11)
	v_mfma_f32_32x32x16_bf16 v[48:63], v[32:35], v[64:67], v[176:191]
	s_waitcnt lgkmcnt(10)
	v_mfma_f32_32x32x16_bf16 v[48:63], v[128:131], v[68:71], v[48:63]
	s_waitcnt lgkmcnt(9)
	v_mfma_f32_32x32x16_bf16 v[48:63], v[132:135], v[72:75], v[48:63]
	s_waitcnt lgkmcnt(8)
	v_mfma_f32_32x32x16_bf16 v[48:63], v[136:139], v[88:91], v[48:63]
	s_waitcnt lgkmcnt(7)
	v_mfma_f32_32x32x16_bf16 v[48:63], v[140:143], v[96:99], v[48:63]
	s_waitcnt lgkmcnt(6)
	v_mfma_f32_32x32x16_bf16 v[48:63], v[144:147], v[100:103], v[48:63]
	s_waitcnt lgkmcnt(5)
	v_mfma_f32_32x32x16_bf16 v[32:47], v[36:39], v[64:67], v[176:191]
	s_waitcnt lgkmcnt(4)
	v_mfma_f32_32x32x16_bf16 v[32:47], v[148:151], v[68:71], v[32:47]
	s_nop 11
	v_exp_f32_e32 v48, v48
	v_exp_f32_e32 v49, v49
	v_exp_f32_e32 v50, v50
	v_exp_f32_e32 v51, v51
	v_exp_f32_e32 v52, v52
	v_exp_f32_e32 v53, v53
	v_exp_f32_e32 v54, v54
	v_exp_f32_e32 v55, v55
	s_waitcnt lgkmcnt(3)
	v_mfma_f32_32x32x16_bf16 v[32:47], v[152:155], v[72:75], v[32:47]
	v_exp_f32_e32 v56, v56
	v_exp_f32_e32 v57, v57
	v_exp_f32_e32 v58, v58
	v_exp_f32_e32 v59, v59
	v_exp_f32_e32 v60, v60
	v_exp_f32_e32 v61, v61
	v_exp_f32_e32 v62, v62
	v_exp_f32_e32 v63, v63
	s_waitcnt lgkmcnt(2)
	v_mfma_f32_32x32x16_bf16 v[32:47], v[156:159], v[88:91], v[32:47]
	v_add_f32_e32 v195, v48, v49
	v_add_f32_e32 v195, v195, v50
	v_add_f32_e32 v195, v195, v51
	v_add_f32_e32 v195, v195, v52
	v_add_f32_e32 v195, v195, v53
	v_add_f32_e32 v195, v195, v54
	v_add_f32_e32 v195, v195, v55
	v_add_f32_e32 v195, v195, v56
	s_waitcnt lgkmcnt(1)
	v_mfma_f32_32x32x16_bf16 v[32:47], v[214:217], v[96:99], v[32:47]
	v_add_f32_e32 v195, v195, v57
	v_add_f32_e32 v195, v195, v58
	v_add_f32_e32 v195, v195, v59
	v_add_f32_e32 v195, v195, v60
	v_add_f32_e32 v195, v195, v61
	v_add_f32_e32 v195, v195, v62
	v_add_f32_e32 v195, v195, v63
	s_waitcnt lgkmcnt(0)
	v_mfma_f32_32x32x16_bf16 v[32:47], v[234:237], v[100:103], v[32:47]
	s_nop 3
	ds_read_b128 v[152:155], v211 offset:52736
	ds_read_b128 v[156:159], v211 offset:44032
	ds_read_b128 v[148:151], v211 offset:44064
	ds_read_b128 v[144:147], v211 offset:52768
	ds_read_b128 v[140:143], v211 offset:44096
	ds_read_b128 v[136:139], v211 offset:52800
	ds_read_b128 v[132:135], v211 offset:44128
	ds_read_b128 v[128:131], v211 offset:52832
	v_exp_f32_e32 v32, v32
	v_exp_f32_e32 v33, v33
	v_exp_f32_e32 v34, v34
	v_exp_f32_e32 v35, v35
	v_exp_f32_e32 v36, v36
	v_exp_f32_e32 v37, v37
	v_exp_f32_e32 v38, v38
	v_exp_f32_e32 v39, v39
	v_exp_f32_e32 v40, v40
	v_exp_f32_e32 v41, v41
	v_exp_f32_e32 v42, v42
	v_exp_f32_e32 v43, v43
	v_exp_f32_e32 v44, v44
	v_exp_f32_e32 v45, v45
	v_exp_f32_e32 v46, v46
	v_exp_f32_e32 v47, v47
	v_add_f32_e32 v195, v195, v32
	v_add_f32_e32 v195, v195, v33
	v_add_f32_e32 v195, v195, v34
	v_add_f32_e32 v195, v195, v35
	v_add_f32_e32 v195, v195, v36
	v_add_f32_e32 v195, v195, v37
	v_add_f32_e32 v195, v195, v38
	v_add_f32_e32 v195, v195, v39
	v_add_f32_e32 v195, v195, v40
	v_add_f32_e32 v195, v195, v41
	v_add_f32_e32 v195, v195, v42
	v_add_f32_e32 v195, v195, v43
	v_add_f32_e32 v195, v195, v44
	v_add_f32_e32 v195, v195, v45
	v_add_f32_e32 v195, v195, v46
	v_add_f32_e32 v195, v195, v47
	v_cmp_nle_f32_e32 vcc, v195, v167
	s_cbranch_vccnz .Lsc0_fb2
	v_add_f32_e32 v213, v213, v195
	v_cvt_pk_bf16_f32 v48, v48, v49
	v_cvt_pk_bf16_f32 v49, v50, v51
	v_cvt_pk_bf16_f32 v50, v52, v53
	v_cvt_pk_bf16_f32 v51, v54, v55
	v_cvt_pk_bf16_f32 v52, v56, v57
	v_cvt_pk_bf16_f32 v53, v58, v59
	v_cvt_pk_bf16_f32 v54, v60, v61
	v_cvt_pk_bf16_f32 v55, v62, v63
	v_cvt_pk_bf16_f32 v56, v32, v33
	v_cvt_pk_bf16_f32 v57, v34, v35
	v_cvt_pk_bf16_f32 v58, v36, v37
	v_cvt_pk_bf16_f32 v59, v38, v39
	v_cvt_pk_bf16_f32 v60, v40, v41
	v_cvt_pk_bf16_f32 v61, v42, v43
	v_cvt_pk_bf16_f32 v62, v44, v45
	v_cvt_pk_bf16_f32 v63, v46, v47
	s_waitcnt lgkmcnt(6)
	v_mfma_f32_32x32x16_bf16 v[16:31], v[156:159], v[48:51], v[16:31]
	v_mfma_f32_32x32x16_bf16 v[0:15], v[152:155], v[48:51], v[0:15]
	s_waitcnt lgkmcnt(5)
	v_mfma_f32_32x32x16_bf16 v[16:31], v[148:151], v[52:55], v[16:31]
	s_waitcnt lgkmcnt(4)
	v_mfma_f32_32x32x16_bf16 v[0:15], v[144:147], v[52:55], v[0:15]
	s_waitcnt lgkmcnt(3)
	v_mfma_f32_32x32x16_bf16 v[16:31], v[140:143], v[56:59], v[16:31]
	s_waitcnt lgkmcnt(2)
	v_mfma_f32_32x32x16_bf16 v[0:15], v[136:139], v[56:59], v[0:15]
	s_waitcnt lgkmcnt(1)
	s_nop 0
	v_mfma_f32_32x32x16_bf16 v[16:31], v[132:135], v[60:63], v[16:31]
	ds_read_b128 v[36:39], v210 offset:57344
	ds_read_b128 v[132:135], v210 offset:57376
	ds_read_b128 v[136:139], v210 offset:57408
	ds_read_b128 v[140:143], v210 offset:57440
	ds_read_b128 v[144:147], v210 offset:57472
	ds_read_b128 v[148:151], v210 offset:57504
	ds_read_b128 v[40:43], v210 offset:64000
	ds_read_b128 v[152:155], v210 offset:64032
	ds_read_b128 v[156:159], v210 offset:64064
	ds_read_b128 v[216:219], v210 offset:64096
	ds_read_b128 v[234:237], v210 offset:64128
	ds_read_b128 v[238:241], v210 offset:64160
	s_waitcnt lgkmcnt(12)
	v_mfma_f32_32x32x16_bf16 v[0:15], v[128:131], v[60:63], v[0:15]
; DI void phase_attn(const Params& p, int hf, bool skipctx, char* smem, int& rot) {
;     ...
;           for (int kb = 0; kb < 2; ++kb) st[kb] = MFMA(kf[kb][ks], qf[ks], st[kb]);
;         __builtin_amdgcn_sched_barrier(0);
;       }
;       bf16x8 vf[2][2][2];
; #pragma unroll
;       for (int kb = 0; kb < 2; ++kb)
; #pragma unroll
;         for (int s2 = 0; s2 < 2; ++s2)
; #pragma unroll
;           for (int dvb = 0; dvb < 2; ++dvb) {
;             const char* vp = sv + (dvb * 32 + r) * VROW + (kb * 32 + 16 * s2 + 4 * h) * 2;
;             const s16x4 lo = *(const s16x4*)vp, hi = *(const s16x4*)(vp + 16);
;             vf[kb][s2][dvb] = __builtin_shufflevector(lo, hi, 0, 1, 2, 3, 4, 5, 6, 7);
;           }
;       float mx = st[0][0];
; #pragma unroll
;       for (int i = 0; i < 16; ++i) { mx = fmaxf(mx, st[0][i]); mx = fmaxf(mx, st[1][i]); }
;       if (__any(mx > m_run + 8.f)) {
;         mx = fmaxf(mx, __shfl_xor(mx, 32));
;         const float m_new = fmaxf(m_run, mx);
;         const float alpha = fexp2(m_run - m_new);
;         m_run = m_new;
;         l_run *= alpha;
; #pragma unroll
;         for (int i = 0; i < 16; ++i) { o[0][i] *= alpha; o[1][i] *= alpha; }
;       }
;       float ps = 0.f;
; #pragma unroll
;       for (int kb = 0; kb < 2; ++kb)
; #pragma unroll
;         for (int i = 0; i < 16; ++i) { const float e = fexp2(st[kb][i] - m_run); st[kb][i] = e; ps += e; }
;       l_run += ps;
; #pragma unroll
;       for (int kb = 0; kb < 2; ++kb)
; #pragma unroll
;         for (int s2 = 0; s2 < 2; ++s2) {
;           const bf16x8 pb = pack8(st[kb][8 * s2 + 0], st[kb][8 * s2 + 1], st[kb][8 * s2 + 2], st[kb][8 * s2 + 3], st[kb][8 * s2 + 4], st[kb][8 * s2 + 5], st[kb][8 * s2 + 6], st[kb][8 * s2 + 7]);
; #pragma unroll
;           for (int dvb = 0; dvb < 2; ++dvb) o[dvb] = MFMA(vf[kb][s2][dvb], pb, o[dvb]);
;         }
;     };
;     __syncthreads();
;     ATT_LOAD(ak0, ak1, ak2, av0, av1, 0);
;     ATT_LOAD(bk0, bk1, bk2, bv0, bv1, 1);
;     ATT_WRITE(ak0, ak1, ak2, av0, av1, 0);
;     __syncthreads();
;     for (int kt = 0; kt < nkt; kt += 2) {
;       if (kt + 2 < nkt) ATT_LOAD(ak0, ak1, ak2, av0, av1, kt + 2);
;       compute(0, 0); compute(0, 1);
;       ATT_WRITE(bk0, bk1, bk2, bv0, bv1, 1);
;       __syncthreads();
;       if (kt + 3 < nkt) ATT_LOAD(bk0, bk1, bk2, bv0, bv1, kt + 3);
;       compute(1, 0); compute(1, 1);
.Lsc0_mj2:
	s_waitcnt lgkmcnt(11)
	v_mfma_f32_32x32x16_bf16 v[48:63], v[36:39], v[64:67], v[176:191]
	s_waitcnt lgkmcnt(10)
	v_mfma_f32_32x32x16_bf16 v[48:63], v[132:135], v[68:71], v[48:63]
	s_waitcnt lgkmcnt(9)
	v_mfma_f32_32x32x16_bf16 v[48:63], v[136:139], v[72:75], v[48:63]
	s_waitcnt lgkmcnt(8)
	v_mfma_f32_32x32x16_bf16 v[48:63], v[140:143], v[88:91], v[48:63]
	s_waitcnt lgkmcnt(7)
	v_mfma_f32_32x32x16_bf16 v[48:63], v[144:147], v[96:99], v[48:63]
	s_waitcnt lgkmcnt(6)
	v_mfma_f32_32x32x16_bf16 v[48:63], v[148:151], v[100:103], v[48:63]
	s_waitcnt lgkmcnt(5)
	v_mfma_f32_32x32x16_bf16 v[32:47], v[40:43], v[64:67], v[176:191]
	s_waitcnt lgkmcnt(4)
	v_mfma_f32_32x32x16_bf16 v[32:47], v[152:155], v[68:71], v[32:47]
	s_nop 11
	v_exp_f32_e32 v48, v48
	v_exp_f32_e32 v49, v49
	v_exp_f32_e32 v50, v50
	v_exp_f32_e32 v51, v51
	v_exp_f32_e32 v52, v52
	v_exp_f32_e32 v53, v53
	v_exp_f32_e32 v54, v54
	v_exp_f32_e32 v55, v55
	s_waitcnt lgkmcnt(3)
	v_mfma_f32_32x32x16_bf16 v[32:47], v[156:159], v[72:75], v[32:47]
	v_exp_f32_e32 v56, v56
	v_exp_f32_e32 v57, v57
	v_exp_f32_e32 v58, v58
	v_exp_f32_e32 v59, v59
	v_exp_f32_e32 v60, v60
	v_exp_f32_e32 v61, v61
	v_exp_f32_e32 v62, v62
	v_exp_f32_e32 v63, v63
	s_waitcnt lgkmcnt(2)
	v_mfma_f32_32x32x16_bf16 v[32:47], v[216:219], v[88:91], v[32:47]
	v_add_f32_e32 v195, v48, v49
	v_add_f32_e32 v195, v195, v50
	v_add_f32_e32 v195, v195, v51
	v_add_f32_e32 v195, v195, v52
	v_add_f32_e32 v195, v195, v53
	v_add_f32_e32 v195, v195, v54
	v_add_f32_e32 v195, v195, v55
	v_add_f32_e32 v195, v195, v56
	s_waitcnt lgkmcnt(1)
	v_mfma_f32_32x32x16_bf16 v[32:47], v[234:237], v[96:99], v[32:47]
	v_add_f32_e32 v195, v195, v57
	v_add_f32_e32 v195, v195, v58
	v_add_f32_e32 v195, v195, v59
	v_add_f32_e32 v195, v195, v60
	v_add_f32_e32 v195, v195, v61
	v_add_f32_e32 v195, v195, v62
	v_add_f32_e32 v195, v195, v63
	s_waitcnt lgkmcnt(0)
	v_mfma_f32_32x32x16_bf16 v[32:47], v[238:241], v[100:103], v[32:47]
	s_nop 3
	ds_read_b128 v[152:155], v211 offset:52864
	ds_read_b128 v[156:159], v211 offset:44160
	ds_read_b128 v[148:151], v211 offset:44192
	ds_read_b128 v[144:147], v211 offset:52896
	ds_read_b128 v[140:143], v211 offset:44224
	ds_read_b128 v[136:139], v211 offset:52928
	ds_read_b128 v[132:135], v211 offset:44256
	ds_read_b128 v[128:131], v211 offset:52960
	v_exp_f32_e32 v32, v32
	v_exp_f32_e32 v33, v33
	v_exp_f32_e32 v34, v34
	v_exp_f32_e32 v35, v35
	v_exp_f32_e32 v36, v36
	v_exp_f32_e32 v37, v37
	v_exp_f32_e32 v38, v38
	v_exp_f32_e32 v39, v39
	v_exp_f32_e32 v40, v40
	v_exp_f32_e32 v41, v41
	v_exp_f32_e32 v42, v42
	v_exp_f32_e32 v43, v43
	v_exp_f32_e32 v44, v44
	v_exp_f32_e32 v45, v45
	v_exp_f32_e32 v46, v46
	v_exp_f32_e32 v47, v47
	v_add_f32_e32 v195, v195, v32
	v_add_f32_e32 v195, v195, v33
	v_add_f32_e32 v195, v195, v34
	v_add_f32_e32 v195, v195, v35
	v_add_f32_e32 v195, v195, v36
	v_add_f32_e32 v195, v195, v37
	v_add_f32_e32 v195, v195, v38
	v_add_f32_e32 v195, v195, v39
	v_add_f32_e32 v195, v195, v40
	v_add_f32_e32 v195, v195, v41
	v_add_f32_e32 v195, v195, v42
	v_add_f32_e32 v195, v195, v43
	v_add_f32_e32 v195, v195, v44
	v_add_f32_e32 v195, v195, v45
	v_add_f32_e32 v195, v195, v46
	v_add_f32_e32 v195, v195, v47
	v_cmp_nle_f32_e32 vcc, v195, v167
	s_cbranch_vccnz .Lsc0_fb3
	v_add_f32_e32 v213, v213, v195
	v_cvt_pk_bf16_f32 v48, v48, v49
	v_cvt_pk_bf16_f32 v49, v50, v51
	v_cvt_pk_bf16_f32 v50, v52, v53
	v_cvt_pk_bf16_f32 v51, v54, v55
	v_cvt_pk_bf16_f32 v52, v56, v57
	v_cvt_pk_bf16_f32 v53, v58, v59
	v_cvt_pk_bf16_f32 v54, v60, v61
	v_cvt_pk_bf16_f32 v55, v62, v63
	v_cvt_pk_bf16_f32 v56, v32, v33
	v_cvt_pk_bf16_f32 v57, v34, v35
	v_cvt_pk_bf16_f32 v58, v36, v37
	v_cvt_pk_bf16_f32 v59, v38, v39
	v_cvt_pk_bf16_f32 v60, v40, v41
	v_cvt_pk_bf16_f32 v61, v42, v43
	v_cvt_pk_bf16_f32 v62, v44, v45
	v_cvt_pk_bf16_f32 v63, v46, v47
	s_waitcnt lgkmcnt(6)
	s_nop 0
	v_mfma_f32_32x32x16_bf16 v[16:31], v[156:159], v[48:51], v[16:31]
	v_mfma_f32_32x32x16_bf16 v[0:15], v[152:155], v[48:51], v[0:15]
	s_waitcnt lgkmcnt(5)
	s_nop 0
	v_mfma_f32_32x32x16_bf16 v[16:31], v[148:151], v[52:55], v[16:31]
	s_waitcnt lgkmcnt(4)
	v_mfma_f32_32x32x16_bf16 v[0:15], v[144:147], v[52:55], v[0:15]
	s_waitcnt lgkmcnt(3)
	s_nop 0
	v_mfma_f32_32x32x16_bf16 v[16:31], v[140:143], v[56:59], v[16:31]
	s_waitcnt lgkmcnt(2)
	v_mfma_f32_32x32x16_bf16 v[0:15], v[136:139], v[56:59], v[0:15]
	s_andn2_b64 vcc, exec, s[36:37]
	s_waitcnt lgkmcnt(1)
	v_mfma_f32_32x32x16_bf16 v[16:31], v[132:135], v[60:63], v[16:31]
	s_waitcnt lgkmcnt(0)
	v_mfma_f32_32x32x16_bf16 v[0:15], v[128:131], v[60:63], v[0:15]
	s_cbranch_vccnz .LBB0_809
	ds_write_b128 v194, v[76:79]
	ds_write_b128 v204, v[80:83]
	ds_write_b128 v206, v[84:87]
	ds_write_b64 v208, v[92:93] offset:0
	ds_write_b64 v208, v[94:95] offset:16
	ds_write_b64 v208, v[104:105] offset:8704
	ds_write_b64 v208, v[106:107] offset:8720
